# v007 + next-tile K/V LDS-DMA issued by waves 4-7 inside their PV MFMA gaps + QK blocks: K reads before V prefetch, 4-VALU K addressing, two-chain row-sum without s_nop
# speedup vs baseline: 1.0329x; 1.0057x over previous
.LBB0_596:
	ds_read_b64_tr_b16 v[112:113], v206 offset:57344
	ds_read_b64_tr_b16 v[114:115], v206 offset:59392
	v_cvt_pk_bf16_f32 v96, v96, v97
	v_cvt_pk_bf16_f32 v97, v98, v99
	v_cvt_pk_bf16_f32 v98, v102, v103
	v_cvt_pk_bf16_f32 v99, v104, v101
	ds_read_b64_tr_b16 v[118:119], v206 offset:61440
	ds_read_b64_tr_b16 v[120:121], v206 offset:63488
	s_waitcnt lgkmcnt(2)
	v_mfma_f32_32x32x16_bf16 v[48:63], v[112:115], v[96:99], v[48:63]
	ds_read_b64_tr_b16 v[112:113], v207 offset:57344
	ds_read_b64_tr_b16 v[114:115], v207 offset:59392
	ds_read_b64_tr_b16 v[122:123], v207 offset:61440
	ds_read_b64_tr_b16 v[124:125], v207 offset:63488
	s_add_u32 s36, s6, 0x30000
	s_addc_u32 s37, s7, 0
	s_add_u32 s38, s0, 0x20000
	v_add_f32_e32 v162, v117, v116
	s_addc_u32 s39, s1, 0
	s_mov_b32 s46, 1
	s_waitcnt lgkmcnt(2)
	v_mfma_f32_32x32x16_bf16 v[32:47], v[112:115], v[96:99], v[32:47]
	ds_read_b64_tr_b16 v[112:113], v208 offset:57344
	ds_read_b64_tr_b16 v[114:115], v208 offset:59392
	ds_read_b64_tr_b16 v[210:211], v208 offset:61440
	ds_read_b64_tr_b16 v[212:213], v208 offset:63488
	s_mov_b32 s65, 3
	s_mov_b32 s69, 0x8000
	s_movk_i32 s70, 0x80
	s_mov_b32 s71, 2
	s_waitcnt lgkmcnt(2)
	v_mfma_f32_32x32x16_bf16 v[16:31], v[112:115], v[96:99], v[16:31]
	ds_read_b64_tr_b16 v[112:113], v209 offset:57344
	ds_read_b64_tr_b16 v[114:115], v209 offset:59392
	ds_read_b64_tr_b16 v[206:207], v209 offset:61440
	ds_read_b64_tr_b16 v[208:209], v209 offset:63488
	s_waitcnt vmcnt(0) lgkmcnt(0)
	s_barrier
	s_waitcnt lgkmcnt(2)
	v_mfma_f32_32x32x16_bf16 v[0:15], v[112:115], v[96:99], v[0:15]
	v_cvt_pk_bf16_f32 v96, v100, v105
	v_cvt_pk_bf16_f32 v97, v106, v107
	v_cvt_pk_bf16_f32 v98, v108, v109
	v_cvt_pk_bf16_f32 v99, v110, v111
	v_cndmask_b32_e64 v100, 0, 1, s[8:9]
	s_nop 0
	v_readfirstlane_b32 s61, v100
	v_mfma_f32_32x32x16_bf16 v[48:63], v[118:121], v[96:99], v[48:63]
	v_mfma_f32_32x32x16_bf16 v[32:47], v[122:125], v[96:99], v[32:47]
	v_mfma_f32_32x32x16_bf16 v[16:31], v[210:213], v[96:99], v[16:31]
	s_waitcnt lgkmcnt(0)
	v_mfma_f32_32x32x16_bf16 v[0:15], v[206:209], v[96:99], v[0:15]
.LBB0_598:
	s_add_i32 s0, s65, -2
	s_cmp_gt_u32 s0, 61
	s_cbranch_scc1 .LBB0_600
	s_mul_i32 s0, s65, 0xab
	s_bfe_u32 s0, s0, 0x70009
	s_mul_i32 s0, s0, 3
	s_sub_i32 s0, s65, s0
	s_and_b32 s0, s0, 0xff
	s_lshl_b32 s0, s0, 14
	s_add_i32 s0, s82, s0
	s_mov_b32 s1, m0
	s_mov_b32 m0, s0
	s_nop 0
	global_load_lds_dwordx4 v174, s[36:37]
	s_mov_b32 m0, s1
	s_addk_i32 s0, 0x2000
	s_mov_b32 s1, m0
	s_mov_b32 m0, s0
	s_nop 0
	global_load_lds_dwordx4 v180, s[36:37]
	s_mov_b32 m0, s1
.LBB0_600:
	s_and_b32 s0, s69, 0x4000
	s_add_i32 s0, s83, s0
	s_mov_b32 s1, m0
	s_mov_b32 m0, s0
	s_nop 0
	global_load_lds_dwordx4 v175, s[38:39]
	s_mov_b32 m0, s1
	s_addk_i32 s0, 0x2000
	s_mov_b32 s1, m0
	s_mov_b32 m0, s0
	s_nop 0
	global_load_lds_dwordx4 v181, s[38:39]
	s_mov_b32 m0, s1
	s_branch .Lat_top
.LBB0_597:
	s_setprio 0
	s_and_b64 vcc, exec, s[98:99]
	v_cvt_pk_bf16_f32 v96, v112, v113
	v_cvt_pk_bf16_f32 v97, v116, v115
	v_cvt_pk_bf16_f32 v98, v118, v119
	v_cvt_pk_bf16_f32 v99, v120, v117
	v_cvt_pk_bf16_f32 v100, v114, v121
	v_cvt_pk_bf16_f32 v101, v122, v123
	v_cvt_pk_bf16_f32 v102, v124, v125
	v_cvt_pk_bf16_f32 v103, v126, v127
	ds_read_b64_tr_b16 v[104:105], v244 offset:61440
	ds_read_b64_tr_b16 v[106:107], v244 offset:63488
	ds_read_b64_tr_b16 v[108:109], v245 offset:61440
	ds_read_b64_tr_b16 v[110:111], v245 offset:63488
	ds_read_b64_tr_b16 v[112:113], v246 offset:61440
	ds_read_b64_tr_b16 v[114:115], v246 offset:63488
	ds_read_b64_tr_b16 v[116:117], v247 offset:61440
	ds_read_b64_tr_b16 v[118:119], v247 offset:63488
	s_add_i32 s65, s65, 1
	s_add_u32 s36, s36, 0x10000
	s_addc_u32 s37, s37, 0
	s_addk_i32 s69, 0x4000
	s_add_i32 s70, s70, 64
	s_add_u32 s38, s38, 0x10000
	s_addc_u32 s39, s39, 0
	s_add_i32 s71, s71, 1
	s_add_i32 s46, s46, 1
	v_add_f32_e32 v162, v163, v162
	s_cbranch_vccz .Lat_lower
	s_mul_i32 s0, s65, 0xab
	s_bfe_u32 s0, s0, 0x70009
	s_mul_i32 s0, s0, 3
	s_sub_i32 s0, s65, s0
	s_and_b32 s0, s0, 0xff
	s_lshl_b32 s0, s0, 14
	s_add_i32 s0, s82, s0
	s_sub_u32 s100, s36, 0x4000
	s_subb_u32 s101, s37, 0
	s_waitcnt vmcnt(0) lgkmcnt(0)
	s_barrier
	v_mfma_f32_32x32x16_bf16 v[48:63], v[228:231], v[96:99], v[48:63]
	s_mov_b32 m0, s0
	s_add_i32 s1, s0, 0x2000
	global_load_lds_dwordx4 v174, s[36:37]
	v_mfma_f32_32x32x16_bf16 v[32:47], v[232:235], v[96:99], v[32:47]
	s_mov_b32 m0, s1
	s_add_i32 s1, s0, 0xfffff000
	global_load_lds_dwordx4 v180, s[36:37]
	v_mfma_f32_32x32x16_bf16 v[16:31], v[236:239], v[96:99], v[16:31]
	s_mov_b32 m0, s1
	s_add_i32 s1, s1, 0x2000
	global_load_lds_dwordx4 v174, s[100:101]
	v_mfma_f32_32x32x16_bf16 v[0:15], v[240:243], v[96:99], v[0:15]
	s_mov_b32 m0, s1
	s_and_b32 s0, s69, 0x4000
	s_add_i32 s0, s83, s0
	global_load_lds_dwordx4 v180, s[100:101]
	v_mfma_f32_32x32x16_bf16 v[48:63], v[104:107], v[100:103], v[48:63]
	s_mov_b32 m0, s0
	s_sub_u32 s100, s38, 0x4000
	s_subb_u32 s101, s39, 0
	s_add_i32 s1, s0, 0x2000
	global_load_lds_dwordx4 v175, s[38:39]
	v_mfma_f32_32x32x16_bf16 v[32:47], v[108:111], v[100:103], v[32:47]
	s_mov_b32 m0, s1
	s_add_i32 s1, s0, 0xfffff000
	global_load_lds_dwordx4 v181, s[38:39]
	v_mfma_f32_32x32x16_bf16 v[16:31], v[112:115], v[100:103], v[16:31]
	s_mov_b32 m0, s1
	s_add_i32 s1, s1, 0x2000
	global_load_lds_dwordx4 v175, s[100:101]
	v_mfma_f32_32x32x16_bf16 v[0:15], v[116:119], v[100:103], v[0:15]
	s_mov_b32 m0, s1
	s_nop 0
	global_load_lds_dwordx4 v181, s[100:101]
	s_branch .Lat_join
.Lat_lower:
	v_mfma_f32_32x32x16_bf16 v[48:63], v[228:231], v[96:99], v[48:63]
	v_mfma_f32_32x32x16_bf16 v[32:47], v[232:235], v[96:99], v[32:47]
	v_mfma_f32_32x32x16_bf16 v[16:31], v[236:239], v[96:99], v[16:31]
	v_mfma_f32_32x32x16_bf16 v[0:15], v[240:243], v[96:99], v[0:15]
	s_waitcnt lgkmcnt(6)
	v_mfma_f32_32x32x16_bf16 v[48:63], v[104:107], v[100:103], v[48:63]
	s_waitcnt lgkmcnt(4)
	v_mfma_f32_32x32x16_bf16 v[32:47], v[108:111], v[100:103], v[32:47]
	s_waitcnt lgkmcnt(2)
	v_mfma_f32_32x32x16_bf16 v[16:31], v[112:115], v[100:103], v[16:31]
	s_waitcnt lgkmcnt(0)
	v_mfma_f32_32x32x16_bf16 v[0:15], v[116:119], v[100:103], v[0:15]
	s_waitcnt vmcnt(0) lgkmcnt(0)
	s_barrier
.Lat_join:
	s_cmp_eq_u32 s69, 0x100000
	s_cbranch_scc1 .LBB0_614
.Lat_top:
	s_add_i32 s62, s55, s70
	s_sub_i32 s8, s62, 64
	s_sub_i32 s33, s62, 63
	s_cmpk_gt_i32 s33, 0x5a
	s_cselect_b64 s[0:1], -1, 0
	s_and_b64 s[6:7], s[0:1], exec
	s_cselect_b32 s60, 2, 1
	s_cmpk_gt_i32 s8, 0xff66
	s_cselect_b64 s[6:7], -1, 0
	s_and_b64 s[8:9], s[6:7], exec
	s_cselect_b32 s60, s60, 0
	s_cmp_eq_u32 s60, s61
	s_cbranch_scc1 .LBB0_602
	s_and_b64 vcc, s[6:7], s[0:1]
	s_cmp_eq_u32 s61, 0
	v_cndmask_b32_e32 v96, 0, v161, vcc
	s_cselect_b64 vcc, -1, 0
	s_cmp_eq_u32 s61, 2
	s_cselect_b64 s[8:9], -1, 0
	v_cndmask_b32_e64 v97, 0, v161, s[8:9]
	v_cndmask_b32_e64 v96, v160, v96, s[6:7]
	v_cndmask_b32_e32 v97, v97, v160, vcc
	v_sub_f32_e32 v96, v96, v97
	v_pk_add_f32 v[78:79], v[78:79], v[96:97] op_sel_hi:[1,0]
	v_pk_add_f32 v[76:77], v[76:77], v[96:97] op_sel_hi:[1,0]
	v_pk_add_f32 v[74:75], v[74:75], v[96:97] op_sel_hi:[1,0]
	v_pk_add_f32 v[72:73], v[72:73], v[96:97] op_sel_hi:[1,0]
	v_pk_add_f32 v[70:71], v[70:71], v[96:97] op_sel_hi:[1,0]
	v_pk_add_f32 v[68:69], v[68:69], v[96:97] op_sel_hi:[1,0]
	v_pk_add_f32 v[66:67], v[66:67], v[96:97] op_sel_hi:[1,0]
	v_pk_add_f32 v[64:65], v[64:65], v[96:97] op_sel_hi:[1,0]
	s_branch .LBB0_603

.LBB0_605:
	s_setprio 1
	s_mul_hi_u32 s0, s46, 0xaaaaaaab
	s_lshr_b32 s0, s0, 1
	s_mul_i32 s0, s0, 0xffff4000
	s_add_i32 s0, s0, s57
	s_add_i32 s0, s0, s69
	v_add3_u32 v96, v193, s0, v173
	v_add3_u32 v122, v191, s0, v173
	v_add3_u32 v248, v192, s0, v173
	v_add3_u32 v249, v190, s0, v173
	ds_read_b128 v[114:117], v96
	ds_read_b128 v[122:125], v122
	ds_read_b128 v[118:121], v248
	ds_read_b128 v[206:209], v249
	s_add_i32 s0, s69, 0xffffc000
	s_and_b32 s0, s0, 0x4000
	v_add_u32_e32 v244, s0, v176
	v_add_u32_e32 v245, s0, v177
	v_add_u32_e32 v246, s0, v178
	v_add_u32_e32 v247, s0, v179
	ds_read_b64_tr_b16 v[228:229], v244 offset:49152
	ds_read_b64_tr_b16 v[230:231], v244 offset:51200
	ds_read_b64_tr_b16 v[232:233], v245 offset:49152
	ds_read_b64_tr_b16 v[234:235], v245 offset:51200
	ds_read_b64_tr_b16 v[236:237], v246 offset:49152
	ds_read_b64_tr_b16 v[238:239], v246 offset:51200
	ds_read_b64_tr_b16 v[240:241], v247 offset:49152
	ds_read_b64_tr_b16 v[242:243], v247 offset:51200
	v_exp_f32_e32 v112, v80
	v_exp_f32_e32 v113, v81
	s_waitcnt lgkmcnt(11)
	v_mfma_f32_32x32x16_bf16 v[96:111], v[114:117], v[140:143], v[64:79]
	v_exp_f32_e32 v114, v82
	v_exp_f32_e32 v115, v83
	v_exp_f32_e32 v116, v84
	v_exp_f32_e32 v117, v85
	v_add_f32_e32 v252, v112, v113
	s_waitcnt lgkmcnt(9)
	v_mfma_f32_32x32x16_bf16 v[96:111], v[118:121], v[136:139], v[96:111]
	v_exp_f32_e32 v118, v86
	v_exp_f32_e32 v119, v87
	v_add_f32_e32 v253, v114, v115
	v_exp_f32_e32 v120, v88
	v_add_f32_e32 v252, v116, v252
	v_exp_f32_e32 v121, v89
	v_add_f32_e32 v253, v117, v253
	v_mfma_f32_32x32x16_bf16 v[96:111], v[122:125], v[132:135], v[96:111]
	v_exp_f32_e32 v122, v90
	v_add_f32_e32 v252, v118, v252
	v_exp_f32_e32 v123, v91
	v_add_f32_e32 v253, v119, v253
	v_exp_f32_e32 v124, v92
	v_add_f32_e32 v252, v120, v252
	v_exp_f32_e32 v125, v93
	v_add_f32_e32 v253, v121, v253
	s_waitcnt lgkmcnt(8)
	v_mfma_f32_32x32x16_bf16 v[96:111], v[206:209], v[128:131], v[96:111]
	v_exp_f32_e32 v126, v94
	v_add_f32_e32 v252, v122, v252
	v_exp_f32_e32 v127, v95
	v_add_f32_e32 v253, v123, v253
	v_add_f32_e32 v252, v124, v252
	v_add_f32_e32 v253, v125, v253
	v_add_f32_e32 v252, v126, v252
	v_add_f32_e32 v253, v127, v253
	v_add_f32_e32 v209, v252, v253
	v_cmp_nge_f32_e32 vcc, s56, v209
	s_cbranch_vccz .LBB0_607
	v_max_f32_e32 v112, v81, v81
	v_max_f32_e32 v113, v80, v80
	v_max_f32_e32 v112, v113, v112
	v_max3_f32 v112, v112, v82, v83
	v_max3_f32 v112, v112, v84, v85
	v_max3_f32 v112, v112, v86, v87
	v_max3_f32 v112, v112, v88, v89
	v_max3_f32 v112, v112, v90, v91
	v_max3_f32 v112, v112, v92, v93
	v_max3_f32 v112, v112, v94, v95
	v_mov_b32_e32 v113, v112
	s_nop 1
	v_permlane32_swap_b32_e32 v112, v113
	v_max3_f32 v121, v112, v113, 0
	v_sub_f32_e32 v80, v80, v121
	v_exp_f32_e32 v112, v80
	v_sub_f32_e32 v81, v81, v121
	v_exp_f32_e32 v113, v81
	v_sub_f32_e32 v81, v82, v121
	v_exp_f32_e32 v114, v81
	v_sub_f32_e32 v81, v83, v121
	v_exp_f32_e32 v115, v81
	v_sub_f32_e32 v81, v84, v121
	v_add_f32_e32 v117, 0, v112
	v_exp_f32_e32 v116, v81
	v_sub_f32_e32 v82, v85, v121
	v_add_f32_e32 v81, v113, v117
	v_exp_f32_e32 v117, v82
	v_sub_f32_e32 v82, v86, v121
	v_add_f32_e32 v81, v114, v81
	v_exp_f32_e32 v118, v82
	v_sub_f32_e32 v82, v87, v121
	v_add_f32_e32 v81, v115, v81
	v_exp_f32_e32 v119, v82
	v_sub_f32_e32 v82, v88, v121
	v_add_f32_e32 v81, v116, v81
	v_sub_f32_e32 v83, v89, v121
	v_exp_f32_e32 v120, v82
	v_exp_f32_e64 v80, -v121
	v_sub_f32_e32 v84, v90, v121
	v_sub_f32_e32 v85, v91, v121
	v_sub_f32_e32 v86, v92, v121
	v_sub_f32_e32 v87, v93, v121
	v_sub_f32_e32 v88, v94, v121
	v_sub_f32_e32 v89, v95, v121
	v_add_f32_e32 v81, v117, v81
	v_sub_f32_e32 v111, v111, v121
	v_sub_f32_e32 v110, v110, v121
	v_sub_f32_e32 v109, v109, v121
	v_sub_f32_e32 v108, v108, v121
	v_sub_f32_e32 v107, v107, v121
	v_sub_f32_e32 v106, v106, v121
	v_sub_f32_e32 v105, v105, v121
	v_sub_f32_e32 v104, v104, v121
	v_sub_f32_e32 v103, v103, v121
	v_sub_f32_e32 v102, v102, v121
	v_sub_f32_e32 v101, v101, v121
	v_sub_f32_e32 v100, v100, v121
	v_sub_f32_e32 v99, v99, v121
	v_sub_f32_e32 v98, v98, v121
	v_sub_f32_e32 v97, v97, v121
	v_sub_f32_e32 v96, v96, v121
	v_sub_f32_e32 v79, v79, v121
	v_sub_f32_e32 v78, v78, v121
	v_sub_f32_e32 v77, v77, v121
	v_sub_f32_e32 v76, v76, v121
	v_sub_f32_e32 v75, v75, v121
	v_sub_f32_e32 v74, v74, v121
	v_sub_f32_e32 v73, v73, v121
	v_sub_f32_e32 v72, v72, v121
	v_sub_f32_e32 v71, v71, v121
	v_sub_f32_e32 v70, v70, v121
	v_sub_f32_e32 v69, v69, v121
	v_sub_f32_e32 v68, v68, v121
	v_sub_f32_e32 v67, v67, v121
	v_sub_f32_e32 v66, v66, v121
	v_sub_f32_e32 v65, v65, v121
	v_sub_f32_e32 v64, v64, v121
	v_exp_f32_e32 v121, v83
	v_add_f32_e32 v81, v118, v81
	v_exp_f32_e32 v122, v84
	v_add_f32_e32 v81, v119, v81
	v_exp_f32_e32 v123, v85
	v_add_f32_e32 v81, v120, v81
	v_exp_f32_e32 v124, v86
	v_pk_mul_f32 v[62:63], v[62:63], v[80:81] op_sel_hi:[1,0]
	v_pk_mul_f32 v[60:61], v[60:61], v[80:81] op_sel_hi:[1,0]
	v_pk_mul_f32 v[58:59], v[58:59], v[80:81] op_sel_hi:[1,0]
	v_pk_mul_f32 v[56:57], v[56:57], v[80:81] op_sel_hi:[1,0]
	v_pk_mul_f32 v[54:55], v[54:55], v[80:81] op_sel_hi:[1,0]
	v_pk_mul_f32 v[52:53], v[52:53], v[80:81] op_sel_hi:[1,0]
	v_pk_mul_f32 v[50:51], v[50:51], v[80:81] op_sel_hi:[1,0]
	v_pk_mul_f32 v[48:49], v[48:49], v[80:81] op_sel_hi:[1,0]
	v_pk_mul_f32 v[46:47], v[46:47], v[80:81] op_sel_hi:[1,0]
	v_pk_mul_f32 v[44:45], v[44:45], v[80:81] op_sel_hi:[1,0]
	v_pk_mul_f32 v[42:43], v[42:43], v[80:81] op_sel_hi:[1,0]
	v_pk_mul_f32 v[40:41], v[40:41], v[80:81] op_sel_hi:[1,0]
	v_pk_mul_f32 v[38:39], v[38:39], v[80:81] op_sel_hi:[1,0]
	v_pk_mul_f32 v[36:37], v[36:37], v[80:81] op_sel_hi:[1,0]
	v_pk_mul_f32 v[34:35], v[34:35], v[80:81] op_sel_hi:[1,0]
	v_pk_mul_f32 v[32:33], v[32:33], v[80:81] op_sel_hi:[1,0]
	v_pk_mul_f32 v[30:31], v[30:31], v[80:81] op_sel_hi:[1,0]
	v_pk_mul_f32 v[28:29], v[28:29], v[80:81] op_sel_hi:[1,0]
	v_pk_mul_f32 v[26:27], v[26:27], v[80:81] op_sel_hi:[1,0]
	v_pk_mul_f32 v[24:25], v[24:25], v[80:81] op_sel_hi:[1,0]
	v_pk_mul_f32 v[22:23], v[22:23], v[80:81] op_sel_hi:[1,0]
	v_pk_mul_f32 v[20:21], v[20:21], v[80:81] op_sel_hi:[1,0]
	v_pk_mul_f32 v[18:19], v[18:19], v[80:81] op_sel_hi:[1,0]
	v_pk_mul_f32 v[16:17], v[16:17], v[80:81] op_sel_hi:[1,0]
	v_pk_mul_f32 v[14:15], v[14:15], v[80:81] op_sel_hi:[1,0]
	v_pk_mul_f32 v[12:13], v[12:13], v[80:81] op_sel_hi:[1,0]
	v_pk_mul_f32 v[10:11], v[10:11], v[80:81] op_sel_hi:[1,0]
	v_pk_mul_f32 v[8:9], v[8:9], v[80:81] op_sel_hi:[1,0]
	v_pk_mul_f32 v[6:7], v[6:7], v[80:81] op_sel_hi:[1,0]
	v_pk_mul_f32 v[4:5], v[4:5], v[80:81] op_sel_hi:[1,0]
	v_pk_mul_f32 v[2:3], v[2:3], v[80:81] op_sel_hi:[1,0]
	v_pk_mul_f32 v[0:1], v[0:1], v[80:81] op_sel_hi:[1,0]
	v_mul_f32_e32 v162, v162, v80
	v_add_f32_e32 v80, v121, v81
	v_exp_f32_e32 v125, v87
	v_add_f32_e32 v80, v122, v80
	v_exp_f32_e32 v126, v88
	v_add_f32_e32 v80, v123, v80
	v_exp_f32_e32 v127, v89
	v_add_f32_e32 v80, v124, v80
	v_add_f32_e32 v80, v125, v80
	v_add_f32_e32 v80, v126, v80
	v_add_f32_e32 v209, v127, v80
.LBB0_607:
	s_setprio 0
	v_cvt_pk_bf16_f32 v80, v112, v113
	v_cvt_pk_bf16_f32 v81, v114, v115
	v_cvt_pk_bf16_f32 v82, v116, v117
	v_cvt_pk_bf16_f32 v83, v118, v119
	ds_read_b64_tr_b16 v[88:89], v244 offset:53248
	ds_read_b64_tr_b16 v[90:91], v244 offset:55296
	ds_read_b64_tr_b16 v[92:93], v245 offset:53248
	ds_read_b64_tr_b16 v[94:95], v245 offset:55296
	v_cvt_pk_bf16_f32 v84, v120, v121
	v_cvt_pk_bf16_f32 v85, v122, v123
	v_cvt_pk_bf16_f32 v86, v124, v125
	v_cvt_pk_bf16_f32 v87, v126, v127
	ds_read_b64_tr_b16 v[112:113], v246 offset:53248
	ds_read_b64_tr_b16 v[114:115], v246 offset:55296
	ds_read_b64_tr_b16 v[116:117], v247 offset:53248
	ds_read_b64_tr_b16 v[118:119], v247 offset:55296
	s_waitcnt lgkmcnt(8)
	v_mfma_f32_32x32x16_bf16 v[48:63], v[228:231], v[80:83], v[48:63]
	s_cmp_gt_u32 s70, s66
	s_cselect_b64 s[0:1], -1, 0
	s_and_b64 s[8:9], s[0:1], exec
	s_cselect_b32 s61, 2, 1
	v_mfma_f32_32x32x16_bf16 v[32:47], v[232:235], v[80:83], v[32:47]
	s_cmp_gt_i32 s70, s68
	s_cselect_b64 vcc, -1, 0
	s_and_b64 s[8:9], vcc, exec
	s_cselect_b32 s61, s61, 0
	v_mfma_f32_32x32x16_bf16 v[16:31], v[236:239], v[80:83], v[16:31]
	s_cmp_eq_u32 s61, s60
	v_mfma_f32_32x32x16_bf16 v[0:15], v[240:243], v[80:83], v[0:15]
	s_waitcnt lgkmcnt(6)
	v_mfma_f32_32x32x16_bf16 v[48:63], v[88:91], v[84:87], v[48:63]
	s_waitcnt lgkmcnt(4)
	v_mfma_f32_32x32x16_bf16 v[32:47], v[92:95], v[84:87], v[32:47]
	s_waitcnt lgkmcnt(2)
	v_mfma_f32_32x32x16_bf16 v[16:31], v[112:115], v[84:87], v[16:31]
	s_waitcnt lgkmcnt(0)
	v_mfma_f32_32x32x16_bf16 v[0:15], v[116:119], v[84:87], v[0:15]
	s_cbranch_scc1 .LBB0_609
	s_and_b64 s[8:9], vcc, s[0:1]
	v_cndmask_b32_e64 v80, 0, v161, s[8:9]
	s_cmp_eq_u32 s60, 0
	v_cndmask_b32_e32 v80, v160, v80, vcc
	s_cselect_b64 vcc, -1, 0
	s_cmp_eq_u32 s60, 2
	s_cselect_b64 s[8:9], -1, 0
	v_cndmask_b32_e64 v81, 0, v161, s[8:9]
	v_cndmask_b32_e32 v81, v81, v160, vcc
	v_sub_f32_e32 v80, v80, v81
	v_pk_add_f32 v[78:79], v[80:81], v[78:79] op_sel_hi:[0,1]
	v_pk_add_f32 v[76:77], v[80:81], v[76:77] op_sel_hi:[0,1]
	v_pk_add_f32 v[74:75], v[80:81], v[74:75] op_sel_hi:[0,1]
	v_pk_add_f32 v[72:73], v[80:81], v[72:73] op_sel_hi:[0,1]
	v_pk_add_f32 v[70:71], v[80:81], v[70:71] op_sel_hi:[0,1]
	v_pk_add_f32 v[68:69], v[80:81], v[68:69] op_sel_hi:[0,1]
	v_pk_add_f32 v[66:67], v[80:81], v[66:67] op_sel_hi:[0,1]
	v_pk_add_f32 v[64:65], v[80:81], v[64:65] op_sel_hi:[0,1]
	s_branch .LBB0_610

.LBB0_612:
	s_setprio 1
	s_mul_hi_u32 s0, s71, 0xaaaaaaab
	s_lshr_b32 s0, s0, 1
	s_mul_i32 s0, s0, 0xffff4000
	s_add_i32 s0, s0, s69
	v_add3_u32 v80, v193, s0, v173
	v_add3_u32 v81, v192, s0, v173
	ds_read_b128 v[112:115], v80
	ds_read_b128 v[120:123], v81
	ds_read_b64_tr_b16 v[228:229], v244 offset:57344
	ds_read_b64_tr_b16 v[230:231], v244 offset:59392
	ds_read_b64_tr_b16 v[232:233], v245 offset:57344
	ds_read_b64_tr_b16 v[234:235], v245 offset:59392
	ds_read_b64_tr_b16 v[236:237], v246 offset:57344
	ds_read_b64_tr_b16 v[238:239], v246 offset:59392
	ds_read_b64_tr_b16 v[240:241], v247 offset:57344
	ds_read_b64_tr_b16 v[242:243], v247 offset:59392
	v_exp_f32_e32 v116, v98
	v_exp_f32_e32 v118, v100
	v_exp_f32_e32 v119, v101
	v_exp_f32_e32 v117, v103
	v_add_f32_e32 v162, v209, v162
	s_waitcnt lgkmcnt(9)
	v_mfma_f32_32x32x16_bf16 v[80:95], v[112:115], v[140:143], v[64:79]
	v_exp_f32_e32 v112, v96
	v_exp_f32_e32 v113, v97
	v_exp_f32_e32 v115, v99
	v_add3_u32 v114, v191, s0, v173
	ds_read_b128 v[124:127], v114
	s_waitcnt lgkmcnt(9)
	v_mfma_f32_32x32x16_bf16 v[80:95], v[120:123], v[136:139], v[80:95]
	v_add_f32_e32 v252, v112, v113
	v_add_f32_e32 v253, v116, v115
	v_exp_f32_e32 v120, v102
	v_add_f32_e32 v252, v118, v252
	v_add3_u32 v122, v190, s0, v173
	v_add_f32_e32 v253, v119, v253
	ds_read_b128 v[210:213], v122
	v_exp_f32_e32 v114, v104
	v_add_f32_e32 v252, v120, v252
	v_exp_f32_e32 v121, v105
	v_add_f32_e32 v253, v117, v253
	v_exp_f32_e32 v122, v106
	v_add_f32_e32 v252, v114, v252
	v_add_f32_e32 v253, v121, v253
	s_waitcnt lgkmcnt(1)
	v_mfma_f32_32x32x16_bf16 v[80:95], v[124:127], v[132:135], v[80:95]
	v_exp_f32_e32 v123, v107
	v_add_f32_e32 v252, v122, v252
	v_exp_f32_e32 v124, v108
	s_waitcnt lgkmcnt(0)
	v_mfma_f32_32x32x16_bf16 v[80:95], v[210:213], v[128:131], v[80:95]
	v_exp_f32_e32 v125, v109
	v_add_f32_e32 v253, v123, v253
	v_exp_f32_e32 v126, v110
	v_add_f32_e32 v252, v124, v252
	v_exp_f32_e32 v127, v111
	v_add_f32_e32 v253, v125, v253
	v_add_f32_e32 v252, v126, v252
	v_add_f32_e32 v253, v127, v253
	v_add_f32_e32 v163, v252, v253
	v_cmp_nge_f32_e32 vcc, s56, v163
	s_cbranch_vccz .LBB0_597
	v_max_f32_e32 v112, v97, v97
	v_max_f32_e32 v113, v96, v96
	v_max_f32_e32 v112, v113, v112
	v_max3_f32 v112, v112, v98, v99
	v_max3_f32 v112, v112, v100, v101
	v_max3_f32 v112, v112, v102, v103
	v_max3_f32 v112, v112, v104, v105
	v_max3_f32 v112, v112, v106, v107
	v_max3_f32 v112, v112, v108, v109
	v_max3_f32 v112, v112, v110, v111
	v_mov_b32_e32 v113, v112
	s_nop 1
	v_permlane32_swap_b32_e32 v112, v113
	v_max3_f32 v121, v112, v113, 0
	v_sub_f32_e32 v96, v96, v121
	v_exp_f32_e32 v112, v96
	v_sub_f32_e32 v97, v97, v121
	v_exp_f32_e32 v113, v97
	v_sub_f32_e32 v97, v98, v121
	v_exp_f32_e32 v116, v97
	v_sub_f32_e32 v97, v99, v121
	v_exp_f32_e32 v115, v97
	v_sub_f32_e32 v97, v100, v121
	v_add_f32_e32 v114, 0, v112
	v_exp_f32_e32 v118, v97
	v_sub_f32_e32 v98, v101, v121
	v_add_f32_e32 v97, v113, v114
	v_exp_f32_e32 v119, v98
	v_sub_f32_e32 v98, v102, v121
	v_add_f32_e32 v97, v116, v97
	v_exp_f32_e32 v120, v98
	v_sub_f32_e32 v98, v103, v121
	v_add_f32_e32 v97, v115, v97
	v_exp_f32_e32 v117, v98
	v_sub_f32_e32 v98, v104, v121
	v_add_f32_e32 v97, v118, v97
	v_sub_f32_e32 v99, v105, v121
	v_exp_f32_e32 v114, v98
	v_exp_f32_e64 v96, -v121
	v_sub_f32_e32 v100, v106, v121
	v_sub_f32_e32 v101, v107, v121
	v_sub_f32_e32 v102, v108, v121
	v_sub_f32_e32 v103, v109, v121
	v_sub_f32_e32 v104, v110, v121
	v_sub_f32_e32 v105, v111, v121
	v_add_f32_e32 v97, v119, v97
	v_sub_f32_e32 v95, v95, v121
	v_sub_f32_e32 v94, v94, v121
	v_sub_f32_e32 v93, v93, v121
	v_sub_f32_e32 v92, v92, v121
	v_sub_f32_e32 v91, v91, v121
	v_sub_f32_e32 v90, v90, v121
	v_sub_f32_e32 v89, v89, v121
	v_sub_f32_e32 v88, v88, v121
	v_sub_f32_e32 v87, v87, v121
	v_sub_f32_e32 v86, v86, v121
	v_sub_f32_e32 v85, v85, v121
	v_sub_f32_e32 v84, v84, v121
	v_sub_f32_e32 v83, v83, v121
	v_sub_f32_e32 v82, v82, v121
	v_sub_f32_e32 v81, v81, v121
	v_sub_f32_e32 v80, v80, v121
	v_sub_f32_e32 v79, v79, v121
	v_sub_f32_e32 v78, v78, v121
	v_sub_f32_e32 v77, v77, v121
	v_sub_f32_e32 v76, v76, v121
	v_sub_f32_e32 v75, v75, v121
	v_sub_f32_e32 v74, v74, v121
	v_sub_f32_e32 v73, v73, v121
	v_sub_f32_e32 v72, v72, v121
	v_sub_f32_e32 v71, v71, v121
	v_sub_f32_e32 v70, v70, v121
	v_sub_f32_e32 v69, v69, v121
	v_sub_f32_e32 v68, v68, v121
	v_sub_f32_e32 v67, v67, v121
	v_sub_f32_e32 v66, v66, v121
	v_sub_f32_e32 v65, v65, v121
	v_sub_f32_e32 v64, v64, v121
	v_exp_f32_e32 v121, v99
	v_add_f32_e32 v97, v120, v97
	v_exp_f32_e32 v122, v100
	v_add_f32_e32 v97, v117, v97
	v_exp_f32_e32 v123, v101
	v_add_f32_e32 v97, v114, v97
	v_exp_f32_e32 v124, v102
	v_pk_mul_f32 v[62:63], v[62:63], v[96:97] op_sel_hi:[1,0]
	v_pk_mul_f32 v[60:61], v[60:61], v[96:97] op_sel_hi:[1,0]
	v_pk_mul_f32 v[58:59], v[58:59], v[96:97] op_sel_hi:[1,0]
	v_pk_mul_f32 v[56:57], v[56:57], v[96:97] op_sel_hi:[1,0]
	v_pk_mul_f32 v[54:55], v[54:55], v[96:97] op_sel_hi:[1,0]
	v_pk_mul_f32 v[52:53], v[52:53], v[96:97] op_sel_hi:[1,0]
	v_pk_mul_f32 v[50:51], v[50:51], v[96:97] op_sel_hi:[1,0]
	v_pk_mul_f32 v[48:49], v[48:49], v[96:97] op_sel_hi:[1,0]
	v_pk_mul_f32 v[46:47], v[46:47], v[96:97] op_sel_hi:[1,0]
	v_pk_mul_f32 v[44:45], v[44:45], v[96:97] op_sel_hi:[1,0]
	v_pk_mul_f32 v[42:43], v[42:43], v[96:97] op_sel_hi:[1,0]
	v_pk_mul_f32 v[40:41], v[40:41], v[96:97] op_sel_hi:[1,0]
	v_pk_mul_f32 v[38:39], v[38:39], v[96:97] op_sel_hi:[1,0]
	v_pk_mul_f32 v[36:37], v[36:37], v[96:97] op_sel_hi:[1,0]
	v_pk_mul_f32 v[34:35], v[34:35], v[96:97] op_sel_hi:[1,0]
	v_pk_mul_f32 v[32:33], v[32:33], v[96:97] op_sel_hi:[1,0]
	v_pk_mul_f32 v[30:31], v[30:31], v[96:97] op_sel_hi:[1,0]
	v_pk_mul_f32 v[28:29], v[28:29], v[96:97] op_sel_hi:[1,0]
	v_pk_mul_f32 v[26:27], v[26:27], v[96:97] op_sel_hi:[1,0]
	v_pk_mul_f32 v[24:25], v[24:25], v[96:97] op_sel_hi:[1,0]
	v_pk_mul_f32 v[22:23], v[22:23], v[96:97] op_sel_hi:[1,0]
	v_pk_mul_f32 v[20:21], v[20:21], v[96:97] op_sel_hi:[1,0]
	v_pk_mul_f32 v[18:19], v[18:19], v[96:97] op_sel_hi:[1,0]
	v_pk_mul_f32 v[16:17], v[16:17], v[96:97] op_sel_hi:[1,0]
	v_pk_mul_f32 v[14:15], v[14:15], v[96:97] op_sel_hi:[1,0]
	v_pk_mul_f32 v[12:13], v[12:13], v[96:97] op_sel_hi:[1,0]
	v_pk_mul_f32 v[10:11], v[10:11], v[96:97] op_sel_hi:[1,0]
	v_pk_mul_f32 v[8:9], v[8:9], v[96:97] op_sel_hi:[1,0]
	v_pk_mul_f32 v[6:7], v[6:7], v[96:97] op_sel_hi:[1,0]
	v_pk_mul_f32 v[4:5], v[4:5], v[96:97] op_sel_hi:[1,0]
	v_pk_mul_f32 v[2:3], v[2:3], v[96:97] op_sel_hi:[1,0]
	v_pk_mul_f32 v[0:1], v[0:1], v[96:97] op_sel_hi:[1,0]
	v_mul_f32_e32 v162, v162, v96
	v_add_f32_e32 v96, v121, v97
	v_exp_f32_e32 v125, v103
	v_add_f32_e32 v96, v122, v96
	v_exp_f32_e32 v126, v104
	v_add_f32_e32 v96, v123, v96
	v_exp_f32_e32 v127, v105
	v_add_f32_e32 v96, v124, v96
	v_add_f32_e32 v96, v125, v96
	v_add_f32_e32 v96, v126, v96
	v_add_f32_e32 v163, v127, v96
	s_branch .LBB0_597

; template <int LO, int HI>
; __global__ void __launch_bounds__(512, 2) mega(Params p) {
;     extern __shared__ __attribute__((aligned(16))) unsigned char lds_raw[];
	.amdhsa_kernel _Z4megaILi0ELi9EEv6Params
		.amdhsa_group_segment_fixed_size 0
		.amdhsa_private_segment_fixed_size 0
		.amdhsa_kernarg_size 440
		.amdhsa_user_sgpr_count 2
		.amdhsa_user_sgpr_dispatch_ptr 0
		.amdhsa_user_sgpr_queue_ptr 0
		.amdhsa_user_sgpr_kernarg_segment_ptr 1
		.amdhsa_user_sgpr_dispatch_id 0
		.amdhsa_user_sgpr_kernarg_preload_length 0
		.amdhsa_user_sgpr_kernarg_preload_offset 0
		.amdhsa_user_sgpr_private_segment_size 0
		.amdhsa_uses_dynamic_stack 0
		.amdhsa_enable_private_segment 0
		.amdhsa_system_sgpr_workgroup_id_x 1
		.amdhsa_system_sgpr_workgroup_id_y 0
		.amdhsa_system_sgpr_workgroup_id_z 0
		.amdhsa_system_sgpr_workgroup_info 0
		.amdhsa_system_vgpr_workitem_id 2
		.amdhsa_next_free_vgpr 256
		.amdhsa_next_free_sgpr 102
		.amdhsa_accum_offset 256
		.amdhsa_reserve_vcc 1
		.amdhsa_float_round_mode_32 0
		.amdhsa_float_round_mode_16_64 0
		.amdhsa_float_denorm_mode_32 3
		.amdhsa_float_denorm_mode_16_64 3
		.amdhsa_dx10_clamp 1
		.amdhsa_ieee_mode 1
		.amdhsa_fp16_overflow 0
		.amdhsa_tg_split 0
		.amdhsa_exception_fp_ieee_invalid_op 0
		.amdhsa_exception_fp_denorm_src 0
		.amdhsa_exception_fp_ieee_div_zero 0
		.amdhsa_exception_fp_ieee_overflow 0
		.amdhsa_exception_fp_ieee_underflow 0
		.amdhsa_exception_fp_ieee_inexact 0
		.amdhsa_exception_int_div_zero 0
	.end_amdhsa_kernel

; template <int LO, int HI>
; __global__ void __launch_bounds__(512, 2) mega(Params p) {
amdhsa.kernels:
  - .agpr_count:     0
    .args:
      - .offset:         0
        .size:           184
        .value_kind:     by_value
      - .offset:         184
        .size:           4
        .value_kind:     hidden_block_count_x
      - .offset:         188
        .size:           4
        .value_kind:     hidden_block_count_y
      - .offset:         192
        .size:           4
        .value_kind:     hidden_block_count_z
      - .offset:         196
        .size:           2
        .value_kind:     hidden_group_size_x
      - .offset:         198
        .size:           2
        .value_kind:     hidden_group_size_y
      - .offset:         200
        .size:           2
        .value_kind:     hidden_group_size_z
      - .offset:         202
        .size:           2
        .value_kind:     hidden_remainder_x
      - .offset:         204
        .size:           2
        .value_kind:     hidden_remainder_y
      - .offset:         206
        .size:           2
        .value_kind:     hidden_remainder_z
      - .offset:         224
        .size:           8
        .value_kind:     hidden_global_offset_x
      - .offset:         232
        .size:           8
        .value_kind:     hidden_global_offset_y
      - .offset:         240
        .size:           8
        .value_kind:     hidden_global_offset_z
      - .offset:         248
        .size:           2
        .value_kind:     hidden_grid_dims
      - .offset:         272
        .size:           8
        .value_kind:     hidden_multigrid_sync_arg
      - .offset:         304
        .size:           4
        .value_kind:     hidden_dynamic_lds_size
    .group_segment_fixed_size: 0
    .kernarg_segment_align: 8
    .kernarg_segment_size: 440
    .language:       OpenCL C
    .language_version:
      - 2
      - 0
    .max_flat_workgroup_size: 512
    .name:           _Z4megaILi0ELi9EEv6Params
    .private_segment_fixed_size: 0
    .sgpr_count:     108
    .sgpr_spill_count: 68
    .symbol:         _Z4megaILi0ELi9EEv6Params.kd
    .uniform_work_group_size: 1
    .uses_dynamic_stack: false
    .vgpr_count:     256
    .vgpr_spill_count: 0
    .wavefront_size: 64
